# indexer loop: key-position load hoisted from mid-tile to the top of the tile (was waited with vmcnt(0) right after issue)
# baseline (speedup 1.0000x reference)
; #define LAS __attribute__((address_space(3)))
; DI void indexer_unit(LAS unsigned char* lds, LAS unsigned long long* smask_w, const bf16_t* PROJ, const bf16_t* KIDXb, const int* posb, int mb0  , int t_0, int njp, int wave, int lane_in) {
;     ...
;     for (int jp = 0; jp < njp; ++jp) {
;         const bool pre = (jp + 1 < njp);
;         u32x4 preg = (u32x4){0u, 0u, 0u, 0u};
;         if (pre) preg = *(const u32x4*)(KIDXb + (size_t)(64 * (jp + 1) + srow) * 64 + sch * 8);
;         const LAS unsigned char* kb = kst + (jp & 1) * 8192;
;         float tot[2][2];
; #pragma unroll
;         for (int hh = 0; hh < 2; ++hh) {
;             const int rowl = 32 * hh + r; const LAS unsigned char* rb = kb + rowl * 128; const int sw = (rowl >> 1) & 7;
;             bf16x8 bk[4];
; #pragma unroll
;             for (int s2 = 0; s2 < 4; ++s2) bk[s2] = *(const LAS bf16x8*)(rb + (((2 * s2 + h) ^ sw) * 16));
; #pragma unroll
;             for (int ct = 0; ct < 2; ++ct) {
;                 f32x16 acc;
; #pragma unroll
;                 for (int i = 0; i < 16; ++i) acc[i] = 0.f;
; #pragma unroll
;                 for (int s2 = 0; s2 < 4; ++s2) acc = __builtin_amdgcn_mfma_f32_32x32x16_bf16(aq[ct][s2], bk[s2], acc, 0, 0, 0);
;                 float p = 0.f;
; #pragma unroll
;                 for (int i = 0; i < 16; ++i) p += wv[ct][i] * __builtin_amdgcn_fmed3f(acc[i], 0.f, __builtin_inff());
;                 p += __shfl_xor(p, 32);
;                 tot[ct][hh] = p;
;             }
;         }
;         const int key = 64 * jp + lane; const int pk = posb[key];
;         sc0[key] = (pk <= pos_t0) ? (h ? tot[0][1] : tot[0][0]) : -INFINITY;
;         sc1[key] = (pk <= pos_t1) ? (h ? tot[1][1] : tot[1][0]) : -INFINITY;
;         if (pre) *(LAS u32x4*)(kst + ((jp + 1) & 1) * 8192 + slo) = preg;
;         __syncthreads();
;     }
.LBB0_528:
	v_ashrrev_i32_e32 v245, 31, v96
	v_mov_b32_e32 v244, v96
	v_lshl_add_u64 v[244:245], v[244:245], 2, s[30:31]
	global_load_dword v243, v[244:245], off
	s_and_b32 s50, s45, 0x2000
	v_add_u32_e32 v4, s50, v133
	v_add_u32_e32 v5, v4, v135
	ds_read_b128 v[0:3], v5
	ds_read_b128 v[86:89], v5 offset:4096
	v_add_u32_e32 v5, v4, v136
	ds_read_b128 v[140:143], v5
	ds_read_b128 v[78:81], v5 offset:4096
	v_add_u32_e32 v5, v4, v137
	s_waitcnt lgkmcnt(3)
	v_mfma_f32_32x32x16_bf16 v[22:37], v[50:53], v[0:3], 0
	ds_read_b128 v[146:149], v5
	ds_read_b128 v[74:77], v5 offset:4096
	v_add_u32_e32 v4, v4, v138
	s_waitcnt lgkmcnt(3)
	v_mfma_f32_32x32x16_bf16 v[22:37], v[38:41], v[140:143], v[22:37]
	v_mfma_f32_32x32x16_bf16 v[6:21], v[62:65], v[0:3], 0
	ds_read_b128 v[0:3], v4
	ds_read_b128 v[82:85], v4 offset:4096
	s_waitcnt lgkmcnt(3)
	v_mfma_f32_32x32x16_bf16 v[22:37], v[42:45], v[146:149], v[22:37]
	v_mfma_f32_32x32x16_bf16 v[6:21], v[54:57], v[140:143], v[6:21]
	s_waitcnt lgkmcnt(1)
	v_mfma_f32_32x32x16_bf16 v[22:37], v[46:49], v[0:3], v[22:37]
	v_mfma_f32_32x32x16_bf16 v[6:21], v[58:61], v[146:149], v[6:21]
	s_nop 10
	v_max_f32_e32 v4, 0, v22
	v_max_f32_e32 v5, 0, v23
	v_max_f32_e32 v22, 0, v24
	v_max_f32_e32 v24, 0, v26
	v_max_f32_e32 v26, 0, v28
	v_max_f32_e32 v28, 0, v30
	v_max_f32_e32 v30, 0, v32
	v_fma_f32 v32, v101, v4, 0
	v_max_f32_e32 v23, 0, v25
	v_fmac_f32_e32 v32, v102, v5
	v_mfma_f32_32x32x16_bf16 v[6:21], v[66:69], v[0:3], v[6:21]
	v_fmac_f32_e32 v32, v103, v22
	v_max_f32_e32 v25, 0, v27
	v_fmac_f32_e32 v32, v104, v23
	v_fmac_f32_e32 v32, v105, v24
	v_max_f32_e32 v27, 0, v29
	v_fmac_f32_e32 v32, v106, v25
	v_fmac_f32_e32 v32, v107, v26
	v_max_f32_e32 v29, 0, v31
	v_fmac_f32_e32 v32, v108, v27
	v_fmac_f32_e32 v32, v109, v28
	v_max_f32_e32 v31, v33, v33
	v_fmac_f32_e32 v32, v110, v29
	v_max_f32_e32 v0, 0, v6
	v_fmac_f32_e32 v32, v111, v30
	v_max_f32_e32 v4, 0, v31
	v_fmac_f32_e32 v32, v112, v4
	v_max_f32_e32 v4, 0, v34
	v_fma_f32 v34, v117, v0, 0
	v_max_f32_e32 v0, 0, v7
	v_fmac_f32_e32 v34, v118, v0
	v_max_f32_e32 v0, 0, v8
	v_fmac_f32_e32 v34, v119, v0
	v_max_f32_e32 v0, 0, v9
	v_fmac_f32_e32 v34, v120, v0
	v_max_f32_e32 v0, 0, v10
	v_fmac_f32_e32 v34, v121, v0
	v_max_f32_e32 v0, 0, v11
	v_fmac_f32_e32 v32, v113, v4
	v_max_f32_e32 v4, 0, v35
	v_fmac_f32_e32 v34, v122, v0
	v_max_f32_e32 v0, 0, v12
	v_fmac_f32_e32 v32, v114, v4
	v_max_f32_e32 v4, 0, v36
	v_fmac_f32_e32 v34, v123, v0
	v_max_f32_e32 v0, 0, v13
	v_fmac_f32_e32 v32, v115, v4
	v_max_f32_e32 v4, 0, v37
	v_fmac_f32_e32 v34, v124, v0
	v_max_f32_e32 v0, 0, v14
	v_fmac_f32_e32 v32, v116, v4
	v_fmac_f32_e32 v34, v125, v0
	v_max_f32_e32 v22, 0, v15
	v_mfma_f32_32x32x16_bf16 v[0:15], v[50:53], v[86:89], 0
	v_max_f32_e32 v16, 0, v16
	v_fmac_f32_e32 v34, v126, v22
	v_fmac_f32_e32 v34, v127, v16
	v_max_f32_e32 v16, 0, v17
	v_mfma_f32_32x32x16_bf16 v[0:15], v[38:41], v[78:81], v[0:15]
	v_fmac_f32_e32 v34, v128, v16
	v_max_f32_e32 v16, 0, v18
	v_fmac_f32_e32 v34, v129, v16
	v_max_f32_e32 v16, 0, v19
	v_fmac_f32_e32 v34, v130, v16
	v_mfma_f32_32x32x16_bf16 v[0:15], v[42:45], v[74:77], v[0:15]
	v_max_f32_e32 v16, 0, v20
	v_fmac_f32_e32 v34, v131, v16
	v_max_f32_e32 v16, 0, v21
	v_fmac_f32_e32 v34, v132, v16
	ds_bpermute_b32 v33, v134, v32
	s_waitcnt lgkmcnt(1)
	v_mfma_f32_32x32x16_bf16 v[0:15], v[46:49], v[82:85], v[0:15]
	ds_bpermute_b32 v35, v134, v34
	v_mfma_f32_32x32x16_bf16 v[16:31], v[62:65], v[86:89], 0
	s_nop 9
	v_max_f32_e32 v0, 0, v0
	v_fma_f32 v36, v101, v0, 0
	v_max_f32_e32 v0, 0, v1
	v_fmac_f32_e32 v36, v102, v0
	v_max_f32_e32 v0, 0, v2
	v_fmac_f32_e32 v36, v103, v0
	v_max_f32_e32 v0, 0, v3
	v_fmac_f32_e32 v36, v104, v0
	v_max_f32_e32 v0, 0, v4
	v_fmac_f32_e32 v36, v105, v0
	v_max_f32_e32 v0, 0, v5
	v_fmac_f32_e32 v36, v106, v0
	v_max_f32_e32 v0, 0, v6
	v_fmac_f32_e32 v36, v107, v0
	v_max_f32_e32 v0, 0, v7
	v_fmac_f32_e32 v36, v108, v0
	v_max_f32_e32 v0, 0, v8
	v_fmac_f32_e32 v36, v109, v0
	v_max_f32_e32 v0, 0, v9
	v_fmac_f32_e32 v36, v110, v0
	v_max_f32_e32 v0, 0, v10
	v_fmac_f32_e32 v36, v111, v0
	v_max_f32_e32 v0, v11, v11
	v_max_f32_e32 v2, 0, v0
	v_mfma_f32_32x32x16_bf16 v[16:31], v[54:57], v[78:81], v[16:31]
	v_fmac_f32_e32 v36, v112, v2
	v_max_f32_e32 v1, 0, v12
	v_fmac_f32_e32 v36, v113, v1
	v_max_f32_e32 v1, 0, v13
	v_fmac_f32_e32 v36, v114, v1
	v_mfma_f32_32x32x16_bf16 v[16:31], v[58:61], v[74:77], v[16:31]
	v_max_f32_e32 v1, 0, v14
	v_fmac_f32_e32 v36, v115, v1
	v_max_f32_e32 v1, 0, v15
	v_fmac_f32_e32 v36, v116, v1
	ds_bpermute_b32 v1, v134, v36
	v_mfma_f32_32x32x16_bf16 v[16:31], v[66:69], v[82:85], v[16:31]
	s_waitcnt lgkmcnt(2)
	v_add_f32_e32 v4, v32, v33
	s_waitcnt lgkmcnt(1)
	v_add_f32_e32 v5, v34, v35
	s_waitcnt lgkmcnt(0)
	v_add_f32_e32 v1, v36, v1
	v_cndmask_b32_e64 v1, v1, v4, s[0:1]
	s_nop 4
	v_max_f32_e32 v2, 0, v16
	v_max_f32_e32 v3, 0, v17
	v_fma_f32 v2, v117, v2, 0
	v_fmac_f32_e32 v2, v118, v3
	v_max_f32_e32 v3, 0, v18
	v_fmac_f32_e32 v2, v119, v3
	v_max_f32_e32 v3, 0, v19
	v_fmac_f32_e32 v2, v120, v3
	v_max_f32_e32 v3, 0, v20
	v_fmac_f32_e32 v2, v121, v3
	v_max_f32_e32 v3, 0, v21
	v_fmac_f32_e32 v2, v122, v3
	v_max_f32_e32 v3, 0, v22
	v_fmac_f32_e32 v2, v123, v3
	v_max_f32_e32 v3, 0, v23
	v_fmac_f32_e32 v2, v124, v3
	v_max_f32_e32 v3, 0, v24
	v_fmac_f32_e32 v2, v125, v3
	v_max_f32_e32 v3, 0, v25
	v_fmac_f32_e32 v2, v126, v3
	v_max_f32_e32 v3, 0, v26
	v_fmac_f32_e32 v2, v127, v3
	v_max_f32_e32 v3, 0, v27
	v_fmac_f32_e32 v2, v128, v3
	v_max_f32_e32 v3, 0, v28
	v_fmac_f32_e32 v2, v129, v3
	v_max_f32_e32 v3, 0, v29
	v_fmac_f32_e32 v2, v130, v3
	v_max_f32_e32 v3, 0, v30
	v_fmac_f32_e32 v2, v131, v3
	v_max_f32_e32 v3, 0, v31
	v_fmac_f32_e32 v2, v132, v3
	ds_bpermute_b32 v3, v134, v2
	s_waitcnt lgkmcnt(0)
	v_add_f32_e32 v2, v2, v3
	v_cndmask_b32_e64 v2, v2, v5, s[0:1]
	s_waitcnt vmcnt(0)
	v_cmp_le_i32_e32 vcc, v243, v90
	s_nop 1
	v_cndmask_b32_e32 v1, v155, v1, vcc
	v_cmp_le_i32_e32 vcc, v243, v91
	s_nop 1
	v_cndmask_b32_e32 v0, v155, v2, vcc
	s_andn2_b64 vcc, exec, s[4:5]
	s_mov_b64 s[4:5], -1
	ds_write2st64_b32 v139, v1, v0 offset1:32
	s_cbranch_vccnz .LBB0_530
	s_add_i32 s50, s45, 0x2000
	s_mov_b64 s[4:5], 0
